# A0 attention: last 8 PV MFMAs of each tile deferred past the barrier into the head of the wave's softmax phase (V fragments held in registers), filling the partner half's startup bubble; A1 stagger +
# baseline (speedup 1.0000x reference)
; DI unsigned cvtpk(float lo, float hi) { f32x2 v = {lo, hi}; return __builtin_bit_cast(unsigned, __builtin_convertvector(v, bf16x2_t)); }
; template <int DQK, int NHQ, int NHKV, bool HAS_META>
; DI void attn_phase(const u16* __restrict__ Q, const u16* __restrict__ K, const u16* __restrict__ Vt, u16* __restrict__ O, const float* __restrict__ qg, const float* __restrict__ kg, char* smem, const int wv) {
;     ...
;     for (int j = 0; j < NT; ++j) {
;       __builtin_amdgcn_s_setprio(0);
;       if (active) {
;         f32x2 ps2 = {0.f, 0.f};
;         unsigned w_[16];
; #pragma unroll
;         for (int i = 0; i < 8; ++i) {
;           f32x2 v;
;           v[0] = __builtin_amdgcn_exp2f(s0[2 * i]); v[1] = __builtin_amdgcn_exp2f(s0[2 * i + 1]);
;           if (j == NT - 1 && i >= 4) v = f32x2{0.f, 0.f};
;           ps2 += v;
;           w_[i] = cvtpk(v[0], v[1]);
;         }
; #pragma unroll
;         for (int i = 0; i < 8; ++i) {
;           f32x2 v;
;           v[0] = __builtin_amdgcn_exp2f(s1[2 * i]); v[1] = __builtin_amdgcn_exp2f(s1[2 * i + 1]);
;           if (j == NT - 1) v = f32x2{0.f, 0.f};
;           ps2 += v;
;           w_[8 + i] = cvtpk(v[0], v[1]);
;         }
;         l += xhalf_sum(ps2[0] + ps2[1]);
;         pb[0] = __builtin_bit_cast(bf16x8, u32x4{w_[0], w_[1], w_[2], w_[3]});
;         pb[1] = __builtin_bit_cast(bf16x8, u32x4{w_[4], w_[5], w_[6], w_[7]});
;         pb[2] = __builtin_bit_cast(bf16x8, u32x4{w_[8], w_[9], w_[10], w_[11]});
;         pb[3] = __builtin_bit_cast(bf16x8, u32x4{w_[12], w_[13], w_[14], w_[15]});
;       }
;     ...
;         for (int i = 0; i < NM; ++i) {
;           if (i < NQK) {
;             if (i & 1) s1 = __builtin_amdgcn_mfma_f32_32x32x16_bf16(ring[i % RING], qf[i >> 1], s1, 0, 0, 0);
;             else       s0 = __builtin_amdgcn_mfma_f32_32x32x16_bf16(ring[i % RING], qf[i >> 1], s0, 0, 0, 0);
;           } else {
;             o[(i - NQK) & 3] = __builtin_amdgcn_mfma_f32_32x32x16_bf16(ring[i % RING], pb[(i - NQK) >> 2], o[(i - NQK) & 3], 0, 0, 0);
;           }
;           if (i + RING < NM) A_FRAG(ring[i % RING], i + RING);
;           __builtin_amdgcn_sched_barrier(0);
;         }
.LBB0_676:
	s_setprio 0
	v_cndmask_b32_e64 v0, 0, 1, s[30:31]
	v_cmp_ne_u32_e64 s[4:5], 1, v0
	s_andn2_b64 vcc, exec, s[30:31]
	s_cbranch_vccnz .LBB0_678
	s_cmp_eq_u32 s59, 0
	s_cbranch_scc1 .Lmy_a0_nodef_loop
	v_mfma_f32_32x32x16_bf16 v[96:111], v[238:241], v[132:135], v[96:111]
	v_mfma_f32_32x32x16_bf16 v[80:95], v[242:245], v[132:135], v[80:95]
	v_mfma_f32_32x32x16_bf16 v[64:79], v[246:249], v[132:135], v[64:79]
	v_mfma_f32_32x32x16_bf16 v[48:63], v[250:253], v[132:135], v[48:63]
	v_mfma_f32_32x32x16_bf16 v[96:111], v[226:229], v[136:139], v[96:111]
	v_mfma_f32_32x32x16_bf16 v[80:95], v[222:225], v[136:139], v[80:95]
	v_mfma_f32_32x32x16_bf16 v[64:79], v[10:13], v[136:139], v[64:79]
	v_mfma_f32_32x32x16_bf16 v[48:63], v[6:9], v[136:139], v[48:63]
.Lmy_a0_nodef_loop:
	v_exp_f32_e32 v2, v16
	v_exp_f32_e32 v3, v17
	v_exp_f32_e32 v4, v18
	v_exp_f32_e32 v5, v19
	v_exp_f32_e32 v8, v22
	v_pk_add_f32 v[6:7], v[2:3], 0 op_sel_hi:[1,0]
	v_cvt_pk_bf16_f32 v112, v2, v3
	v_pk_add_f32 v[2:3], v[4:5], v[6:7]
	v_exp_f32_e32 v6, v20
	v_exp_f32_e32 v7, v21
	v_exp_f32_e32 v9, v23
	v_cvt_pk_bf16_f32 v113, v4, v5
	v_exp_f32_e32 v4, v24
	v_exp_f32_e32 v5, v25
	v_pk_add_f32 v[2:3], v[6:7], v[2:3]
	v_cvt_pk_bf16_f32 v114, v6, v7
	v_pk_add_f32 v[2:3], v[8:9], v[2:3]
	v_exp_f32_e32 v6, v26
	v_exp_f32_e32 v7, v27
	v_pk_add_f32 v[2:3], v[4:5], v[2:3]
	v_cvt_pk_bf16_f32 v128, v4, v5
	v_exp_f32_e32 v4, v28
	v_exp_f32_e32 v5, v29
	v_cvt_pk_bf16_f32 v115, v8, v9
	v_pk_add_f32 v[2:3], v[6:7], v[2:3]
	v_exp_f32_e32 v8, v30
	v_exp_f32_e32 v9, v31
	v_pk_add_f32 v[2:3], v[4:5], v[2:3]
	v_cvt_pk_bf16_f32 v130, v4, v5
	v_exp_f32_e32 v4, v32
	v_exp_f32_e32 v5, v33
	v_cvt_pk_bf16_f32 v129, v6, v7
	v_pk_add_f32 v[2:3], v[8:9], v[2:3]
	v_exp_f32_e32 v6, v34
	v_exp_f32_e32 v7, v35
	v_pk_add_f32 v[2:3], v[4:5], v[2:3]
	v_cvt_pk_bf16_f32 v132, v4, v5
	v_exp_f32_e32 v4, v36
	v_exp_f32_e32 v5, v37
	v_cvt_pk_bf16_f32 v131, v8, v9
	v_pk_add_f32 v[2:3], v[6:7], v[2:3]
	v_exp_f32_e32 v8, v38
	v_exp_f32_e32 v9, v39
	v_pk_add_f32 v[2:3], v[4:5], v[2:3]
	v_cvt_pk_bf16_f32 v134, v4, v5
	v_exp_f32_e32 v4, v40
	v_exp_f32_e32 v5, v41
	v_cvt_pk_bf16_f32 v133, v6, v7
	v_pk_add_f32 v[2:3], v[8:9], v[2:3]
	v_exp_f32_e32 v6, v42
	v_exp_f32_e32 v7, v43
	v_pk_add_f32 v[2:3], v[4:5], v[2:3]
	v_cvt_pk_bf16_f32 v136, v4, v5
	v_exp_f32_e32 v4, v44
	v_exp_f32_e32 v5, v45
	v_cvt_pk_bf16_f32 v135, v8, v9
	v_exp_f32_e32 v8, v46
	v_exp_f32_e32 v9, v47
	v_pk_add_f32 v[2:3], v[6:7], v[2:3]
	v_cvt_pk_bf16_f32 v137, v6, v7
	v_pk_add_f32 v[2:3], v[4:5], v[2:3]
	v_cvt_pk_bf16_f32 v138, v4, v5
	v_pk_add_f32 v[2:3], v[8:9], v[2:3]
	v_cvt_pk_bf16_f32 v139, v8, v9
	v_pk_add_f32 v[2:3], v[2:3], v[2:3] op_sel:[0,1] op_sel_hi:[1,0]
	s_nop 0
	v_mov_b32_e32 v0, v2
	s_nop 1
	v_permlane32_swap_b32_e32 v2, v0
	v_add_f32_e32 v0, v2, v0
	v_add_f32_e32 v221, v221, v0
; #define RAW_BAR() do { asm volatile("s_waitcnt lgkmcnt(0)" ::: "memory"); __builtin_amdgcn_s_barrier(); asm volatile("" ::: "memory"); } while (0)
; #define A_WRITEK(bi_) do { char* b_ = kb0 + (bi_) * KBYTES + kwoff; \
;     _Pragma("unroll") for (int i_ = 0; i_ < NKC; ++i_) *(u32x4*)(b_ + i_ * 128) = rk[i_]; } while (0)
; template <int DQK, int NHQ, int NHKV, bool HAS_META>
; DI void attn_phase(const u16* __restrict__ Q, const u16* __restrict__ K, const u16* __restrict__ Vt, u16* __restrict__ O, const float* __restrict__ qg, const float* __restrict__ kg, char* smem, const int wv) {
;     ...
;       __builtin_amdgcn_s_setprio(2);
;       RAW_BAR();
;       if (j + 2 < NT) A_WRITEK(j & 1);
;       else if (j == NT - 1 && has_next) A_WRITEK(0);
;       if (j + 1 < NT) A_WRITEV((j + 1) & 1);
;       __builtin_amdgcn_sched_barrier(0);
;       if constexpr (EARLY_FETCH) { A_FETCH(j); __builtin_amdgcn_sched_barrier(0); }
;         if (active && j == NT - 1) {
;         const char* svl = vb0 + (j & 1) * VBYTES + r32 * VSTR + hh * 16;
;         bf16x8 vf[4];
; #pragma unroll
;         for (int d = 0; d < 4; ++d) vf[d] = *(const bf16x8*)(svl + d * 32 * VSTR);
; #pragma unroll
;         for (int d = 0; d < 4; ++d) o[d] = __builtin_amdgcn_mfma_f32_32x32x16_bf16(vf[d], pb[0], o[d], 0, 0, 0);
;       } else if (active)
;       {
;         constexpr int NQK = 2 * NS, NM = NQK + 16, RING = (DQK == 128) ? 8 : 6;
;         const char* sk = kb0 + ((j + 1) & 1) * KBYTES + r32 * KSTR + hh * 16;
;         const char* sv = vb0 + (j & 1) * VBYTES + r32 * VSTR + hh * 16;
;         bf16x8 ring[RING];
;     ...
; #pragma unroll
;         for (int i = 0; i < 16; ++i) { s0[i] = 0.f; s1[i] = 0.f; }
; #pragma unroll
;         for (int i = 0; i < RING; ++i) A_FRAG(ring[i], i);
; #pragma unroll
;         for (int i = 0; i < NM; ++i) {
;           if (i < NQK) {
;             if (i & 1) s1 = __builtin_amdgcn_mfma_f32_32x32x16_bf16(ring[i % RING], qf[i >> 1], s1, 0, 0, 0);
;             else       s0 = __builtin_amdgcn_mfma_f32_32x32x16_bf16(ring[i % RING], qf[i >> 1], s0, 0, 0, 0);
;           } else {
;             o[(i - NQK) & 3] = __builtin_amdgcn_mfma_f32_32x32x16_bf16(ring[i % RING], pb[(i - NQK) >> 2], o[(i - NQK) & 3], 0, 0, 0);
;           }
;           if (i + RING < NM) A_FRAG(ring[i % RING], i + RING);
;           __builtin_amdgcn_sched_barrier(0);
;         }
.LBB0_678:
	s_setprio 2
	s_bitcmp1_b32 s59, 0
	s_cselect_b64 s[38:39], -1, 0
	s_and_b64 s[40:41], s[38:39], exec
	s_cselect_b32 s60, 0x6400, 0
	s_add_i32 s61, s59, 1
	s_bitcmp1_b32 s61, 0
	s_cselect_b64 s[40:41], -1, 0
	s_waitcnt lgkmcnt(0)
	s_barrier
	s_and_b64 s[62:63], s[40:41], exec
	v_add_u32_e32 v0, s60, v212
	s_cselect_b32 s62, 0x4800, 0
	s_waitcnt vmcnt(4)
	ds_write_b128 v0, v[116:119]
	s_waitcnt vmcnt(3)
	ds_write_b128 v0, v[120:123] offset:128
	s_waitcnt vmcnt(2)
	ds_write_b128 v0, v[124:127] offset:256
	v_add_u32_e32 v0, s62, v215
	s_waitcnt vmcnt(1)
	ds_write_b128 v0, v[140:143] offset:51200
	s_waitcnt vmcnt(0)
	ds_write_b128 v0, v[144:147] offset:60416
	s_and_b64 vcc, exec, s[4:5]
	s_cbranch_vccnz .LBB0_680
	s_and_b64 s[40:41], s[40:41], exec
	s_cselect_b32 s62, 0x6400, 0
	v_add_u32_e32 v0, s62, v216
	ds_read_b128 v[2:5], v0
	ds_read_b128 v[6:9], v0 offset:32
	ds_read_b128 v[10:13], v0 offset:12800
	ds_read_b128 v[140:143], v0 offset:12832
	ds_read_b128 v[144:147], v0 offset:12864
	ds_read_b128 v[222:225], v0 offset:64
	ds_read_b128 v[226:229], v0 offset:96
	s_and_b64 s[40:41], s[38:39], exec
	s_cselect_b32 s40, 0x4800, 0
	v_add_u32_e32 v14, s40, v217
	s_waitcnt lgkmcnt(6)
	v_mfma_f32_32x32x16_bf16 v[16:31], v[2:5], v[192:195], 0
	s_waitcnt lgkmcnt(4)
	v_mfma_f32_32x32x16_bf16 v[32:47], v[10:13], v[192:195], 0
	ds_read_b128 v[2:5], v0 offset:12896
	v_mfma_f32_32x32x16_bf16 v[16:31], v[6:9], v[188:191], v[16:31]
	ds_read_b128 v[10:13], v0 offset:128
	s_waitcnt lgkmcnt(5)
	v_mfma_f32_32x32x16_bf16 v[32:47], v[140:143], v[188:191], v[32:47]
	ds_read_b128 v[6:9], v0 offset:12928
	s_waitcnt lgkmcnt(4)
	v_mfma_f32_32x32x16_bf16 v[16:31], v[222:225], v[184:187], v[16:31]
	ds_read_b128 v[140:143], v0 offset:160
	v_mfma_f32_32x32x16_bf16 v[32:47], v[144:147], v[184:187], v[32:47]
	ds_read_b128 v[222:225], v0 offset:12960
	s_waitcnt lgkmcnt(5)
	v_mfma_f32_32x32x16_bf16 v[16:31], v[226:229], v[180:183], v[16:31]
	ds_read_b128 v[144:147], v0 offset:192
	s_waitcnt lgkmcnt(5)
	v_mfma_f32_32x32x16_bf16 v[32:47], v[2:5], v[180:183], v[32:47]
	ds_read_b128 v[226:229], v0 offset:12992
	s_waitcnt lgkmcnt(5)
	v_mfma_f32_32x32x16_bf16 v[16:31], v[10:13], v[176:179], v[16:31]
	ds_read_b128 v[2:5], v0 offset:224
	s_waitcnt lgkmcnt(5)
	v_mfma_f32_32x32x16_bf16 v[32:47], v[6:9], v[176:179], v[32:47]
	ds_read_b128 v[10:13], v0 offset:13024
	s_waitcnt lgkmcnt(5)
	v_mfma_f32_32x32x16_bf16 v[16:31], v[140:143], v[172:175], v[16:31]
	ds_read_b128 v[6:9], v0 offset:256
	s_waitcnt lgkmcnt(5)
	v_mfma_f32_32x32x16_bf16 v[32:47], v[222:225], v[172:175], v[32:47]
	ds_read_b128 v[140:143], v0 offset:13056
	s_waitcnt lgkmcnt(5)
	v_mfma_f32_32x32x16_bf16 v[16:31], v[144:147], v[168:171], v[16:31]
	ds_read_b128 v[222:225], v0 offset:288
	s_waitcnt lgkmcnt(5)
	v_mfma_f32_32x32x16_bf16 v[32:47], v[226:229], v[168:171], v[32:47]
	ds_read_b128 v[144:147], v0 offset:13088
	s_waitcnt lgkmcnt(5)
	v_mfma_f32_32x32x16_bf16 v[16:31], v[2:5], v[164:167], v[16:31]
	ds_read_b128 v[226:229], v0 offset:320
	s_waitcnt lgkmcnt(5)
	v_mfma_f32_32x32x16_bf16 v[32:47], v[10:13], v[164:167], v[32:47]
	ds_read_b128 v[2:5], v0 offset:13120
	s_waitcnt lgkmcnt(5)
	v_mfma_f32_32x32x16_bf16 v[16:31], v[6:9], v[160:163], v[16:31]
	ds_read_b128 v[10:13], v0 offset:352
	s_waitcnt lgkmcnt(5)
	v_mfma_f32_32x32x16_bf16 v[32:47], v[140:143], v[160:163], v[32:47]
	ds_read_b128 v[6:9], v0 offset:13152
	s_waitcnt lgkmcnt(5)
	v_mfma_f32_32x32x16_bf16 v[16:31], v[222:225], v[156:159], v[16:31]
	ds_read_b128 v[140:143], v14 offset:51200
	s_waitcnt lgkmcnt(5)
	v_mfma_f32_32x32x16_bf16 v[32:47], v[144:147], v[156:159], v[32:47]
	ds_read_b128 v[222:225], v14 offset:55808
	s_waitcnt lgkmcnt(5)
	v_mfma_f32_32x32x16_bf16 v[16:31], v[226:229], v[152:155], v[16:31]
	ds_read_b128 v[144:147], v14 offset:60416
	s_waitcnt lgkmcnt(5)
	v_mfma_f32_32x32x16_bf16 v[32:47], v[2:5], v[152:155], v[32:47]
	ds_read_b128 v[226:229], v14 offset:65024
	s_waitcnt lgkmcnt(5)
	v_mfma_f32_32x32x16_bf16 v[16:31], v[10:13], v[148:151], v[16:31]
	ds_read_b128 v[2:5], v14 offset:51232
	s_waitcnt lgkmcnt(5)
	v_mfma_f32_32x32x16_bf16 v[32:47], v[6:9], v[148:151], v[32:47]
	ds_read_b128 v[10:13], v14 offset:55840
	s_waitcnt lgkmcnt(5)
	v_mfma_f32_32x32x16_bf16 v[96:111], v[140:143], v[112:115], v[96:111]
	ds_read_b128 v[6:9], v14 offset:60448
	s_waitcnt lgkmcnt(5)
	v_mfma_f32_32x32x16_bf16 v[80:95], v[222:225], v[112:115], v[80:95]
	ds_read_b128 v[140:143], v14 offset:65056
	s_waitcnt lgkmcnt(5)
	v_mfma_f32_32x32x16_bf16 v[64:79], v[144:147], v[112:115], v[64:79]
	ds_read_b128 v[238:241], v14 offset:51264
	ds_read_b128 v[242:245], v14 offset:55872
	s_waitcnt lgkmcnt(6)
	v_mfma_f32_32x32x16_bf16 v[48:63], v[226:229], v[112:115], v[48:63]
	ds_read_b128 v[246:249], v14 offset:60480
	ds_read_b128 v[250:253], v14 offset:65088
	s_waitcnt lgkmcnt(7)
	v_mfma_f32_32x32x16_bf16 v[96:111], v[2:5], v[128:131], v[96:111]
	ds_read_b128 v[226:229], v14 offset:51296
	ds_read_b128 v[222:225], v14 offset:55904
	s_waitcnt lgkmcnt(8)
	v_mfma_f32_32x32x16_bf16 v[80:95], v[10:13], v[128:131], v[80:95]
	ds_read_b128 v[10:13], v14 offset:60512
	s_waitcnt lgkmcnt(8)
	v_mfma_f32_32x32x16_bf16 v[64:79], v[6:9], v[128:131], v[64:79]
	ds_read_b128 v[6:9], v14 offset:65120
	s_waitcnt lgkmcnt(8)
	v_mfma_f32_32x32x16_bf16 v[48:63], v[140:143], v[128:131], v[48:63]
	s_waitcnt lgkmcnt(0)

; DI unsigned cvtpk(float lo, float hi) { f32x2 v = {lo, hi}; return __builtin_bit_cast(unsigned, __builtin_convertvector(v, bf16x2_t)); }
; template <int DQK, int NHQ, int NHKV, bool HAS_META>
; DI void attn_phase(const u16* __restrict__ Q, const u16* __restrict__ K, const u16* __restrict__ Vt, u16* __restrict__ O, const float* __restrict__ qg, const float* __restrict__ kg, char* smem, const int wv) {
;     ...
;     for (int j = 0; j < NT; ++j) {
;       __builtin_amdgcn_s_setprio(0);
;       if (active) {
;         f32x2 ps2 = {0.f, 0.f};
;         unsigned w_[16];
; #pragma unroll
;         for (int i = 0; i < 8; ++i) {
;           f32x2 v;
;           v[0] = __builtin_amdgcn_exp2f(s0[2 * i]); v[1] = __builtin_amdgcn_exp2f(s0[2 * i + 1]);
;           if (j == NT - 1 && i >= 4) v = f32x2{0.f, 0.f};
;           ps2 += v;
;           w_[i] = cvtpk(v[0], v[1]);
;         }
; #pragma unroll
;         for (int i = 0; i < 8; ++i) {
;           f32x2 v;
;           v[0] = __builtin_amdgcn_exp2f(s1[2 * i]); v[1] = __builtin_amdgcn_exp2f(s1[2 * i + 1]);
;           if (j == NT - 1) v = f32x2{0.f, 0.f};
;           ps2 += v;
;           w_[8 + i] = cvtpk(v[0], v[1]);
;         }
;         l += xhalf_sum(ps2[0] + ps2[1]);
;         pb[0] = __builtin_bit_cast(bf16x8, u32x4{w_[0], w_[1], w_[2], w_[3]});
;         pb[1] = __builtin_bit_cast(bf16x8, u32x4{w_[4], w_[5], w_[6], w_[7]});
;         pb[2] = __builtin_bit_cast(bf16x8, u32x4{w_[8], w_[9], w_[10], w_[11]});
;         pb[3] = __builtin_bit_cast(bf16x8, u32x4{w_[12], w_[13], w_[14], w_[15]});
;       }
;     ...
;             o[(i - NQK) & 3] = __builtin_amdgcn_mfma_f32_32x32x16_bf16(ring[i % RING], pb[(i - NQK) >> 2], o[(i - NQK) & 3], 0, 0, 0);
.LBB0_688:
	s_setprio 0
	s_and_b64 vcc, exec, s[4:5]
	s_cbranch_vccnz .LBB0_690
	v_mfma_f32_32x32x16_bf16 v[96:111], v[238:241], v[132:135], v[96:111]
	v_mfma_f32_32x32x16_bf16 v[80:95], v[242:245], v[132:135], v[80:95]
	v_mfma_f32_32x32x16_bf16 v[64:79], v[246:249], v[132:135], v[64:79]
	v_mfma_f32_32x32x16_bf16 v[48:63], v[250:253], v[132:135], v[48:63]
	v_mfma_f32_32x32x16_bf16 v[96:111], v[226:229], v[136:139], v[96:111]
	v_mfma_f32_32x32x16_bf16 v[80:95], v[222:225], v[136:139], v[80:95]
	v_mfma_f32_32x32x16_bf16 v[64:79], v[10:13], v[136:139], v[64:79]
	v_mfma_f32_32x32x16_bf16 v[48:63], v[6:9], v[136:139], v[48:63]
	v_exp_f32_e32 v2, v16
	v_exp_f32_e32 v3, v17
	v_exp_f32_e32 v4, v18
	v_exp_f32_e32 v5, v19
	v_exp_f32_e32 v8, v22
	v_pk_add_f32 v[6:7], v[2:3], 0 op_sel_hi:[1,0]
	v_cvt_pk_bf16_f32 v112, v2, v3
	v_pk_add_f32 v[2:3], v[4:5], v[6:7]
	v_exp_f32_e32 v6, v20
	v_exp_f32_e32 v7, v21
	v_exp_f32_e32 v9, v23
	v_cvt_pk_bf16_f32 v113, v4, v5
	v_exp_f32_e32 v4, v24
	v_exp_f32_e32 v5, v25
	v_pk_add_f32 v[2:3], v[6:7], v[2:3]
	v_cvt_pk_bf16_f32 v114, v6, v7
	v_pk_add_f32 v[2:3], v[8:9], v[2:3]
	v_exp_f32_e32 v6, v26
	v_exp_f32_e32 v7, v27
	v_pk_add_f32 v[2:3], v[4:5], v[2:3]
	v_cvt_pk_bf16_f32 v128, v4, v5
	v_exp_f32_e32 v4, v28
	v_exp_f32_e32 v5, v29
	v_cvt_pk_bf16_f32 v115, v8, v9
	v_pk_add_f32 v[2:3], v[6:7], v[2:3]
	v_exp_f32_e32 v8, v30
	v_exp_f32_e32 v9, v31
	v_pk_add_f32 v[2:3], v[4:5], v[2:3]
	v_cvt_pk_bf16_f32 v130, v4, v5
	v_exp_f32_e32 v4, v32
	v_exp_f32_e32 v5, v33
	v_cvt_pk_bf16_f32 v129, v6, v7
	v_pk_add_f32 v[2:3], v[8:9], v[2:3]
	v_exp_f32_e32 v6, v34
	v_exp_f32_e32 v7, v35
	v_pk_add_f32 v[2:3], v[4:5], v[2:3]
	v_cvt_pk_bf16_f32 v132, v4, v5
	v_exp_f32_e32 v4, v36
	v_exp_f32_e32 v5, v37
	v_cvt_pk_bf16_f32 v131, v8, v9
	v_pk_add_f32 v[2:3], v[6:7], v[2:3]
	v_exp_f32_e32 v8, v38
	v_exp_f32_e32 v9, v39
	v_pk_add_f32 v[2:3], v[4:5], v[2:3]
	v_cvt_pk_bf16_f32 v134, v4, v5
	v_exp_f32_e32 v4, v40
	v_exp_f32_e32 v5, v41
	v_cvt_pk_bf16_f32 v133, v6, v7
	v_pk_add_f32 v[2:3], v[8:9], v[2:3]
	v_exp_f32_e32 v6, v42
	v_exp_f32_e32 v7, v43
	v_pk_add_f32 v[2:3], v[4:5], v[2:3]
	v_cvt_pk_bf16_f32 v136, v4, v5
	v_exp_f32_e32 v4, v44
	v_exp_f32_e32 v5, v45
	v_cvt_pk_bf16_f32 v135, v8, v9
	v_exp_f32_e32 v8, v46
	v_exp_f32_e32 v9, v47
	v_pk_add_f32 v[2:3], v[6:7], v[2:3]
	v_cvt_pk_bf16_f32 v137, v6, v7
	v_pk_add_f32 v[2:3], v[4:5], v[2:3]
	v_cvt_pk_bf16_f32 v138, v4, v5
	v_pk_add_f32 v[2:3], v[8:9], v[2:3]
	v_cvt_pk_bf16_f32 v139, v8, v9
	v_pk_add_f32 v[2:3], v[2:3], v[2:3] op_sel:[0,1] op_sel_hi:[1,0]
	s_nop 0
	v_mov_b32_e32 v0, v2
	s_nop 1
	v_permlane32_swap_b32_e32 v2, v0
	v_add_f32_e32 v0, v2, v0
	v_add_f32_e32 v221, v221, v0

; template <int NHQ, int NHKV>
; DI void attn_phase_l1(const u16* __restrict__ Q, const u16* __restrict__ K, const u16* __restrict__ Vt, u16* __restrict__ O, const float* __restrict__ qg, char* smem, const int wv) {
;     ...
;         constexpr int NQK = 2 * NS, NM = NQK + 16, RING = 8;
;         const char* sk = kb0 + ((j + 1) & 1) * KBYTES + r32 * KSTR + hh * 16;
;         const char* sv = vb0 + (j & 1) * VBYTES + r32 * VSTR + hh * 16;
;         bf16x8 ring[RING];
;         unsigned w_[16]; f32x2 ps2 = {0.f, 0.f};
;     ...
; #pragma unroll
;         for (int i = 0; i < 16; ++i) { s0[i] = 0.f; s1[i] = 0.f; }
; #pragma unroll
;         for (int i = 0; i < RING; ++i) B_FRAG(ring[i], i);
; #pragma unroll
;         for (int i = 0; i < NM; ++i) {
;           if (i < NQK) {
;             if (i & 1) s1 = __builtin_amdgcn_mfma_f32_32x32x16_bf16(ring[i % RING], qf[i >> 1], s1, 0, 0, 0);
;             else       s0 = __builtin_amdgcn_mfma_f32_32x32x16_bf16(ring[i % RING], qf[i >> 1], s0, 0, 0, 0);
;           } else {
;             o[(i - NQK) & 3] = __builtin_amdgcn_mfma_f32_32x32x16_bf16(ring[i % RING], pb[(i - NQK) >> 2], o[(i - NQK) & 3], 0, 0, 0);
;           }
;           if (i + RING < NM) B_FRAG(ring[i % RING], i + RING);
;           if (i >= NQK + 2) {
;             const int g = i - NQK - 2;
;             f32x2 v;
;             if (g < 8) { v[0] = __builtin_amdgcn_exp2f(s0[2 * g]); v[1] = __builtin_amdgcn_exp2f(s0[2 * g + 1]); }
;             else       { v[0] = __builtin_amdgcn_exp2f(s1[2 * (g - 8)]); v[1] = __builtin_amdgcn_exp2f(s1[2 * (g - 8) + 1]); }
;             ps2 += v; w_[g] = cvtpk(v[0], v[1]);
;           }
;           __builtin_amdgcn_sched_barrier(0);
;         }
; #pragma unroll
;         for (int g = 14; g < 16; ++g) { f32x2 v; v[0] = __builtin_amdgcn_exp2f(s1[2 * (g - 8)]); v[1] = __builtin_amdgcn_exp2f(s1[2 * (g - 8) + 1]); ps2 += v; w_[g] = cvtpk(v[0], v[1]); }
;     ...
;         if (j + 1 == NT - 1) {
;           ps2 = f32x2{0.f, 0.f};
; #pragma unroll
;           for (int g = 0; g < 4; ++g) { ps2[0] += __builtin_amdgcn_exp2f(s0[2 * g]); ps2[1] += __builtin_amdgcn_exp2f(s0[2 * g + 1]); }
; #pragma unroll
;           for (int g = 4; g < 16; ++g) w_[g] = 0u;
;         }
;         if (j + 1 < NT) {
;           l += ps2[0] + ps2[1];
; #pragma unroll
.Lmy_a1_skipk:
	v_mfma_f32_32x32x16_bf16 v[64:79], v[214:217], v[104:107], v[64:79]
	v_lshl_add_u64 v[240:241], s[6:7], 0, v[174:175]
	v_add_co_u32_e32 v244, vcc, 0x29900000, v240
	s_nop 1
	v_addc_co_u32_e32 v245, vcc, 0, v241, vcc
	v_add_co_u32_e32 v240, vcc, 0x29982000, v240
	s_nop 1
	v_addc_co_u32_e32 v241, vcc, 0, v241, vcc
	global_load_dwordx4 v[136:139], v[244:245], off offset:256
	global_load_dwordx4 v[140:143], v[240:241], off offset:256
	s_waitcnt lgkmcnt(11)
	v_mfma_f32_32x32x16_bf16 v[80:95], v[220:223], v[116:119], v[80:95]
	ds_read_b128 v[214:217], v177 offset:34816
	ds_read_b128 v[220:223], v177 offset:39424
	s_waitcnt lgkmcnt(11)
	v_mfma_f32_32x32x16_bf16 v[64:79], v[224:227], v[116:119], v[64:79]
	v_mfma_f32_32x32x16_bf16 v[80:95], v[228:231], v[120:123], v[80:95]
	ds_read_b128 v[224:227], v177 offset:44032
	ds_read_b128 v[228:231], v177 offset:48640
	s_waitcnt lgkmcnt(9)
	v_mfma_f32_32x32x16_bf16 v[64:79], v[178:181], v[120:123], v[64:79]
	v_mfma_f32_32x32x16_bf16 v[80:95], v[182:185], v[112:115], v[80:95]
	ds_read_b128 v[178:181], v177 offset:34848
	ds_read_b128 v[182:185], v177 offset:39456
	s_waitcnt lgkmcnt(7)
	v_mfma_f32_32x32x16_bf16 v[64:79], v[190:193], v[112:115], v[64:79]
	v_mfma_f32_32x32x16_bf16 v[80:95], v[186:189], v[124:127], v[80:95]
	ds_read_b128 v[190:193], v177 offset:44064
	ds_read_b128 v[186:189], v177 offset:48672
	s_waitcnt lgkmcnt(7)
	v_mfma_f32_32x32x16_bf16 v[64:79], v[194:197], v[124:127], v[64:79]
	v_mfma_f32_32x32x16_bf16 v[48:63], v[214:217], v[144:147], v[48:63]
	ds_read_b128 v[194:197], v177 offset:34880
	s_waitcnt lgkmcnt(7)
	v_mfma_f32_32x32x16_bf16 v[32:47], v[220:223], v[144:147], v[32:47]
	ds_read_b128 v[214:217], v177 offset:39488
	s_waitcnt lgkmcnt(7)
	v_mfma_f32_32x32x16_bf16 v[16:31], v[224:227], v[144:147], v[16:31]
	v_exp_f32_e32 v80, v80
	v_exp_f32_e32 v81, v81
	ds_read_b128 v[220:223], v177 offset:44096
	v_mov_b32_e32 v198, v80
	v_mov_b32_e32 v199, v81
	v_cvt_pk_bf16_f32 v80, v80, v81
	s_waitcnt lgkmcnt(7)
	v_mfma_f32_32x32x16_bf16 v[0:15], v[228:231], v[144:147], v[0:15]
	v_exp_f32_e32 v82, v82
	v_exp_f32_e32 v83, v83
	ds_read_b128 v[224:227], v177 offset:48704
	v_cvt_pk_bf16_f32 v145, v82, v83
	v_add_f32_e32 v198, v82, v198
	v_add_f32_e32 v199, v83, v199
	s_waitcnt lgkmcnt(7)
	v_mfma_f32_32x32x16_bf16 v[48:63], v[178:181], v[148:151], v[48:63]
	v_exp_f32_e32 v82, v84
	v_exp_f32_e32 v83, v85
	ds_read_b128 v[228:231], v177 offset:34912
	v_add_f32_e32 v84, v82, v198
	v_add_f32_e32 v85, v83, v199
	v_cvt_pk_bf16_f32 v146, v82, v83
	s_waitcnt lgkmcnt(7)
	v_mfma_f32_32x32x16_bf16 v[32:47], v[182:185], v[148:151], v[32:47]
	v_exp_f32_e32 v82, v86
	v_exp_f32_e32 v83, v87
	ds_read_b128 v[178:181], v177 offset:39520
	v_add_f32_e32 v84, v82, v84
	v_add_f32_e32 v85, v83, v85
	v_cvt_pk_bf16_f32 v147, v82, v83
	s_waitcnt lgkmcnt(7)
	v_mfma_f32_32x32x16_bf16 v[16:31], v[190:193], v[148:151], v[16:31]
	v_exp_f32_e32 v82, v88
	v_exp_f32_e32 v83, v89
	ds_read_b128 v[182:185], v177 offset:44128
	v_add_f32_e32 v86, v82, v84
	v_add_f32_e32 v87, v83, v85
	v_cvt_pk_bf16_f32 v84, v82, v83
	s_waitcnt lgkmcnt(7)
	v_mfma_f32_32x32x16_bf16 v[0:15], v[186:189], v[148:151], v[0:15]
	v_exp_f32_e32 v82, v90
	v_exp_f32_e32 v83, v91
	ds_read_b128 v[190:193], v177 offset:48736
	v_cvt_pk_bf16_f32 v149, v82, v83
	v_add_f32_e32 v86, v82, v86
	v_add_f32_e32 v87, v83, v87
	s_waitcnt lgkmcnt(7)
	v_mfma_f32_32x32x16_bf16 v[48:63], v[194:197], v[152:155], v[48:63]
	v_exp_f32_e32 v82, v92
	v_exp_f32_e32 v83, v93
	s_nop 0
	v_cvt_pk_bf16_f32 v150, v82, v83
	v_add_f32_e32 v86, v82, v86
	v_add_f32_e32 v87, v83, v87
	s_waitcnt lgkmcnt(6)
	v_mfma_f32_32x32x16_bf16 v[32:47], v[214:217], v[152:155], v[32:47]
	v_exp_f32_e32 v82, v94
	v_exp_f32_e32 v83, v95
	s_nop 0
	v_cvt_pk_bf16_f32 v151, v82, v83
	v_add_f32_e32 v86, v82, v86
	v_add_f32_e32 v87, v83, v87
	s_waitcnt lgkmcnt(5)
	v_mfma_f32_32x32x16_bf16 v[16:31], v[220:223], v[152:155], v[16:31]
	v_exp_f32_e32 v64, v64
	v_exp_f32_e32 v65, v65
	s_nop 0
	v_cvt_pk_bf16_f32 v88, v64, v65
	v_add_f32_e32 v82, v64, v86
	v_add_f32_e32 v83, v65, v87
	s_waitcnt lgkmcnt(4)
	v_mfma_f32_32x32x16_bf16 v[0:15], v[224:227], v[152:155], v[0:15]
	v_exp_f32_e32 v64, v66
	v_exp_f32_e32 v65, v67
	s_nop 0
	v_cvt_pk_bf16_f32 v153, v64, v65
	v_add_f32_e32 v66, v64, v82
	v_add_f32_e32 v67, v65, v83
	s_waitcnt lgkmcnt(3)
	v_mfma_f32_32x32x16_bf16 v[48:63], v[228:231], v[156:159], v[48:63]
	v_exp_f32_e32 v64, v68
	v_exp_f32_e32 v65, v69
	s_nop 0
	v_cvt_pk_bf16_f32 v154, v64, v65
	v_add_f32_e32 v66, v64, v66
	v_add_f32_e32 v67, v65, v67
	s_waitcnt lgkmcnt(2)
	v_mfma_f32_32x32x16_bf16 v[32:47], v[178:181], v[156:159], v[32:47]
	v_exp_f32_e32 v64, v70
	v_exp_f32_e32 v65, v71
	s_nop 0
	v_cvt_pk_bf16_f32 v155, v64, v65
	v_add_f32_e32 v66, v64, v66
	v_add_f32_e32 v67, v65, v67
	s_waitcnt lgkmcnt(1)
	v_mfma_f32_32x32x16_bf16 v[16:31], v[182:185], v[156:159], v[16:31]
	v_exp_f32_e32 v64, v72
	v_exp_f32_e32 v65, v73
	s_nop 0
	v_cvt_pk_bf16_f32 v92, v64, v65
	v_add_f32_e32 v66, v64, v66
	v_add_f32_e32 v67, v65, v67
	s_waitcnt lgkmcnt(0)
	v_mfma_f32_32x32x16_bf16 v[0:15], v[190:193], v[156:159], v[0:15]
	v_exp_f32_e32 v64, v74
	v_exp_f32_e32 v65, v75
	s_nop 0
	v_cvt_pk_bf16_f32 v157, v64, v65
	v_add_f32_e32 v64, v64, v66
	v_add_f32_e32 v65, v65, v67
	v_exp_f32_e32 v66, v76
	v_exp_f32_e32 v67, v77
	v_exp_f32_e32 v68, v78
	v_exp_f32_e32 v69, v79
	s_waitcnt lgkmcnt(0)
	v_add_f32_e32 v64, v66, v64
	v_add_f32_e32 v65, v67, v65
	s_barrier
	v_add_f32_e32 v64, v68, v64
	v_add_f32_e32 v65, v69, v65
	s_add_u32 s24, s24, 0x8000
	v_add_f32_e32 v64, v64, v65
	s_addc_u32 s25, s25, 0
	v_cvt_pk_bf16_f32 v158, v66, v67
	v_cvt_pk_bf16_f32 v159, v68, v69
	v_add_f32_e32 v176, v176, v64
	s_cmp_eq_u32 s27, 62
	v_lshl_add_u64 v[174:175], v[174:175], 0, s[16:17]
	s_cbranch_scc1 .LBB0_1215
	s_mov_b32 s42, s27
	s_branch .LBB0_1217

; DI unsigned cvtpk(float lo, float hi) { f32x2 v = {lo, hi}; return __builtin_bit_cast(unsigned, __builtin_convertvector(v, bf16x2_t)); }
; template <int NHQ, int NHKV>
; DI void attn_phase_l1(const u16* __restrict__ Q, const u16* __restrict__ K, const u16* __restrict__ Vt, u16* __restrict__ O, const float* __restrict__ qg, char* smem, const int wv) {
;     ...
;           if (i >= NQK + 2) {
;             const int g = i - NQK - 2;
;             f32x2 v;
;             if (g < 8) { v[0] = __builtin_amdgcn_exp2f(s0[2 * g]); v[1] = __builtin_amdgcn_exp2f(s0[2 * g + 1]); }
;             else       { v[0] = __builtin_amdgcn_exp2f(s1[2 * (g - 8)]); v[1] = __builtin_amdgcn_exp2f(s1[2 * (g - 8) + 1]); }
;             ps2 += v; w_[g] = cvtpk(v[0], v[1]);
;           }
;           __builtin_amdgcn_sched_barrier(0);
;         }
; #pragma unroll
;         for (int g = 14; g < 16; ++g) { f32x2 v; v[0] = __builtin_amdgcn_exp2f(s1[2 * (g - 8)]); v[1] = __builtin_amdgcn_exp2f(s1[2 * (g - 8) + 1]); ps2 += v; w_[g] = cvtpk(v[0], v[1]); }
;     ...
;         if (j + 1 == NT - 1) {
;           ps2 = f32x2{0.f, 0.f};
; #pragma unroll
;           for (int g = 0; g < 4; ++g) { ps2[0] += __builtin_amdgcn_exp2f(s0[2 * g]); ps2[1] += __builtin_amdgcn_exp2f(s0[2 * g + 1]); }
; #pragma unroll
;           for (int g = 4; g < 16; ++g) w_[g] = 0u;
;         }
;         if (j + 1 < NT) {
;           l += ps2[0] + ps2[1];
; #pragma unroll
;           for (int q = 0; q < 4; ++q) pb[q] = __builtin_bit_cast(bf16x8, u32x4{w_[4 * q], w_[4 * q + 1], w_[4 * q + 2], w_[4 * q + 3]});
.Lb_top:
	s_nop 7
	v_exp_f32_e32 v246, v80
	v_exp_f32_e32 v247, v81
	s_nop 0
	v_add_f32_e32 v250, 0, v246
	v_add_f32_e32 v251, 0, v247
	v_exp_f32_e32 v248, v82
	v_exp_f32_e32 v249, v83
	v_cvt_pk_bf16_f32 v144, v246, v247
	v_add_f32_e32 v250, v248, v250
	v_add_f32_e32 v251, v249, v251
	v_exp_f32_e32 v246, v84
	v_exp_f32_e32 v247, v85
	v_cvt_pk_bf16_f32 v145, v248, v249
	v_add_f32_e32 v250, v246, v250
	v_add_f32_e32 v251, v247, v251
	v_exp_f32_e32 v248, v86
	v_exp_f32_e32 v249, v87
	v_cvt_pk_bf16_f32 v146, v246, v247
	v_add_f32_e32 v250, v248, v250
	v_add_f32_e32 v251, v249, v251
	v_exp_f32_e32 v246, v88
	v_exp_f32_e32 v247, v89
	v_cvt_pk_bf16_f32 v147, v248, v249
	v_add_f32_e32 v250, v246, v250
	v_add_f32_e32 v251, v247, v251
	v_exp_f32_e32 v248, v90
	v_exp_f32_e32 v249, v91
	v_cvt_pk_bf16_f32 v148, v246, v247
	v_add_f32_e32 v250, v248, v250
	v_add_f32_e32 v251, v249, v251
	v_exp_f32_e32 v246, v92
	v_exp_f32_e32 v247, v93
	v_cvt_pk_bf16_f32 v149, v248, v249
	v_add_f32_e32 v250, v246, v250
	v_add_f32_e32 v251, v247, v251
	v_exp_f32_e32 v248, v94
	v_exp_f32_e32 v249, v95
	v_cvt_pk_bf16_f32 v150, v246, v247
	v_add_f32_e32 v250, v248, v250
	v_add_f32_e32 v251, v249, v251
	v_exp_f32_e32 v246, v64
	v_exp_f32_e32 v247, v65
	v_cvt_pk_bf16_f32 v151, v248, v249
	v_add_f32_e32 v250, v246, v250
	v_add_f32_e32 v251, v247, v251
	v_exp_f32_e32 v248, v66
	v_exp_f32_e32 v249, v67
	v_cvt_pk_bf16_f32 v152, v246, v247
	v_add_f32_e32 v250, v248, v250
	v_add_f32_e32 v251, v249, v251
	v_exp_f32_e32 v246, v68
	v_exp_f32_e32 v247, v69
	v_cvt_pk_bf16_f32 v153, v248, v249
	v_add_f32_e32 v250, v246, v250
	v_add_f32_e32 v251, v247, v251
	v_exp_f32_e32 v248, v70
	v_exp_f32_e32 v249, v71
	v_cvt_pk_bf16_f32 v154, v246, v247
	v_add_f32_e32 v250, v248, v250
	v_add_f32_e32 v251, v249, v251
	v_exp_f32_e32 v246, v72
	v_exp_f32_e32 v247, v73
	v_cvt_pk_bf16_f32 v155, v248, v249
	v_add_f32_e32 v250, v246, v250
	v_add_f32_e32 v251, v247, v251
	v_exp_f32_e32 v248, v74
	v_exp_f32_e32 v249, v75
	v_cvt_pk_bf16_f32 v156, v246, v247
	v_add_f32_e32 v250, v248, v250
	v_add_f32_e32 v251, v249, v251
	v_exp_f32_e32 v246, v76
	v_exp_f32_e32 v247, v77
	v_cvt_pk_bf16_f32 v157, v248, v249
	v_add_f32_e32 v250, v246, v250
	v_add_f32_e32 v251, v247, v251
	v_exp_f32_e32 v248, v78
	v_exp_f32_e32 v249, v79
	v_cvt_pk_bf16_f32 v158, v246, v247
	v_add_f32_e32 v250, v248, v250
	v_add_f32_e32 v251, v249, v251
	v_cvt_pk_bf16_f32 v159, v248, v249
	v_add_f32_e32 v250, v250, v251
	v_add_f32_e32 v176, v176, v250

; DI unsigned cvtpk(float lo, float hi) { f32x2 v = {lo, hi}; return __builtin_bit_cast(unsigned, __builtin_convertvector(v, bf16x2_t)); }
; template <int NHQ, int NHKV>
; DI void attn_phase_l1(const u16* __restrict__ Q, const u16* __restrict__ K, const u16* __restrict__ Vt, u16* __restrict__ O, const float* __restrict__ qg, char* smem, const int wv) {
;     ...
; #pragma unroll
;         for (int i = 0; i < NM; ++i) {
;           if (i < NQK) {
;             if (i & 1) s1 = __builtin_amdgcn_mfma_f32_32x32x16_bf16(ring[i % RING], qf[i >> 1], s1, 0, 0, 0);
;             else       s0 = __builtin_amdgcn_mfma_f32_32x32x16_bf16(ring[i % RING], qf[i >> 1], s0, 0, 0, 0);
;           } else {
;             o[(i - NQK) & 3] = __builtin_amdgcn_mfma_f32_32x32x16_bf16(ring[i % RING], pb[(i - NQK) >> 2], o[(i - NQK) & 3], 0, 0, 0);
;           }
;           if (i + RING < NM) B_FRAG(ring[i % RING], i + RING);
;           if (i >= NQK + 2) {
;             const int g = i - NQK - 2;
;             f32x2 v;
;             if (g < 8) { v[0] = __builtin_amdgcn_exp2f(s0[2 * g]); v[1] = __builtin_amdgcn_exp2f(s0[2 * g + 1]); }
;             else       { v[0] = __builtin_amdgcn_exp2f(s1[2 * (g - 8)]); v[1] = __builtin_amdgcn_exp2f(s1[2 * (g - 8) + 1]); }
;             ps2 += v; w_[g] = cvtpk(v[0], v[1]);
;           }
;           __builtin_amdgcn_sched_barrier(0);
;         }
; #pragma unroll
;         for (int g = 14; g < 16; ++g) { f32x2 v; v[0] = __builtin_amdgcn_exp2f(s1[2 * (g - 8)]); v[1] = __builtin_amdgcn_exp2f(s1[2 * (g - 8) + 1]); ps2 += v; w_[g] = cvtpk(v[0], v[1]); }
;     ...
;         if (j + 1 == NT - 1) {
;           ps2 = f32x2{0.f, 0.f};
; #pragma unroll
;           for (int g = 0; g < 4; ++g) { ps2[0] += __builtin_amdgcn_exp2f(s0[2 * g]); ps2[1] += __builtin_amdgcn_exp2f(s0[2 * g + 1]); }
; #pragma unroll
;           for (int g = 4; g < 16; ++g) w_[g] = 0u;
;         }
;         if (j + 1 < NT) {
;           l += ps2[0] + ps2[1];
; #pragma unroll
;           for (int q = 0; q < 4; ++q) pb[q] = __builtin_bit_cast(bf16x8, u32x4{w_[4 * q], w_[4 * q + 1], w_[4 * q + 2], w_[4 * q + 3]});
;         }
;       }
;       asm volatile("s_waitcnt lgkmcnt(0)" ::: "memory"); __builtin_amdgcn_s_barrier(); asm volatile("" ::: "memory");
.Lmy_b_skipk:
	v_mfma_f32_32x32x16_bf16 v[64:79], v[214:217], v[104:107], v[64:79]
	v_lshl_add_u64 v[240:241], s[6:7], 0, v[174:175]
	v_add_co_u32_e32 v244, vcc, 0x29900000, v240
	s_nop 1
	v_addc_co_u32_e32 v245, vcc, 0, v241, vcc
	v_add_co_u32_e32 v240, vcc, 0x29982000, v240
	s_nop 1
	v_addc_co_u32_e32 v241, vcc, 0, v241, vcc
	global_load_dwordx4 v[136:139], v[244:245], off offset:256
	global_load_dwordx4 v[140:143], v[240:241], off offset:256
	s_waitcnt lgkmcnt(11)
	v_mfma_f32_32x32x16_bf16 v[80:95], v[220:223], v[116:119], v[80:95]
	ds_read_b128 v[214:217], v177 offset:34816
	ds_read_b128 v[220:223], v177 offset:39424
	s_waitcnt lgkmcnt(11)
	v_mfma_f32_32x32x16_bf16 v[64:79], v[224:227], v[116:119], v[64:79]
	v_mfma_f32_32x32x16_bf16 v[80:95], v[228:231], v[120:123], v[80:95]
	ds_read_b128 v[224:227], v177 offset:44032
	ds_read_b128 v[228:231], v177 offset:48640
	s_waitcnt lgkmcnt(9)
	v_mfma_f32_32x32x16_bf16 v[64:79], v[178:181], v[120:123], v[64:79]
	v_mfma_f32_32x32x16_bf16 v[80:95], v[182:185], v[112:115], v[80:95]
	ds_read_b128 v[178:181], v177 offset:34848
	ds_read_b128 v[182:185], v177 offset:39456
	s_waitcnt lgkmcnt(7)
	v_mfma_f32_32x32x16_bf16 v[64:79], v[190:193], v[112:115], v[64:79]
	v_mfma_f32_32x32x16_bf16 v[80:95], v[186:189], v[124:127], v[80:95]
	ds_read_b128 v[190:193], v177 offset:44064
	ds_read_b128 v[186:189], v177 offset:48672
	s_waitcnt lgkmcnt(7)
	v_mfma_f32_32x32x16_bf16 v[64:79], v[194:197], v[124:127], v[64:79]
	v_mfma_f32_32x32x16_bf16 v[48:63], v[214:217], v[144:147], v[48:63]
	ds_read_b128 v[194:197], v177 offset:34880
	s_waitcnt lgkmcnt(7)
	v_mfma_f32_32x32x16_bf16 v[32:47], v[220:223], v[144:147], v[32:47]
	ds_read_b128 v[214:217], v177 offset:39488
	s_waitcnt lgkmcnt(7)
	v_mfma_f32_32x32x16_bf16 v[16:31], v[224:227], v[144:147], v[16:31]
	ds_read_b128 v[220:223], v177 offset:44096
	s_waitcnt lgkmcnt(7)
	v_mfma_f32_32x32x16_bf16 v[0:15], v[228:231], v[144:147], v[0:15]
	ds_read_b128 v[224:227], v177 offset:48704
	s_waitcnt lgkmcnt(7)
	v_mfma_f32_32x32x16_bf16 v[48:63], v[178:181], v[148:151], v[48:63]
	ds_read_b128 v[228:231], v177 offset:34912
	s_waitcnt lgkmcnt(7)
	v_mfma_f32_32x32x16_bf16 v[32:47], v[182:185], v[148:151], v[32:47]
	ds_read_b128 v[178:181], v177 offset:39520
	s_waitcnt lgkmcnt(7)
	v_mfma_f32_32x32x16_bf16 v[16:31], v[190:193], v[148:151], v[16:31]
	ds_read_b128 v[182:185], v177 offset:44128
	s_waitcnt lgkmcnt(7)
	v_mfma_f32_32x32x16_bf16 v[0:15], v[186:189], v[148:151], v[0:15]
	ds_read_b128 v[190:193], v177 offset:48736
	s_waitcnt lgkmcnt(6)
	v_mfma_f32_32x32x16_bf16 v[48:63], v[194:197], v[152:155], v[48:63]
	v_mfma_f32_32x32x16_bf16 v[32:47], v[214:217], v[152:155], v[32:47]
	s_waitcnt lgkmcnt(4)
	v_mfma_f32_32x32x16_bf16 v[16:31], v[220:223], v[152:155], v[16:31]
	v_mfma_f32_32x32x16_bf16 v[0:15], v[224:227], v[152:155], v[0:15]
	s_waitcnt lgkmcnt(2)
	v_mfma_f32_32x32x16_bf16 v[48:63], v[228:231], v[156:159], v[48:63]
	v_mfma_f32_32x32x16_bf16 v[32:47], v[178:181], v[156:159], v[32:47]
	s_waitcnt lgkmcnt(0)
	v_mfma_f32_32x32x16_bf16 v[16:31], v[182:185], v[156:159], v[16:31]
	v_mfma_f32_32x32x16_bf16 v[0:15], v[190:193], v[156:159], v[0:15]
	s_waitcnt lgkmcnt(0)
	s_barrier
	s_add_u32 s24, s24, 0x8000
	s_addc_u32 s25, s25, 0
	s_cmp_eq_u32 s27, 62
	v_lshl_add_u64 v[174:175], v[174:175], 0, s[16:17]
	s_cbranch_scc1 .Lb_exit
	s_mov_b32 s42, s27
	s_branch .Lb_top
.Lb_exit:
	s_nop 7
	v_exp_f32_e32 v246, v80
	v_exp_f32_e32 v247, v81
	s_nop 0
	v_add_f32_e32 v250, 0, v246
	v_add_f32_e32 v251, 0, v247
	v_exp_f32_e32 v248, v82
	v_exp_f32_e32 v249, v83
	v_cvt_pk_bf16_f32 v80, v246, v247
	v_add_f32_e32 v250, v248, v250
	v_add_f32_e32 v251, v249, v251
	v_exp_f32_e32 v246, v84
	v_exp_f32_e32 v247, v85
	v_cvt_pk_bf16_f32 v145, v248, v249
	v_add_f32_e32 v250, v246, v250
	v_add_f32_e32 v251, v247, v251
	v_exp_f32_e32 v248, v86
	v_exp_f32_e32 v249, v87
	v_cvt_pk_bf16_f32 v146, v246, v247
	v_add_f32_e32 v250, v248, v250
	v_add_f32_e32 v251, v249, v251
	v_exp_f32_e32 v246, v88
	v_exp_f32_e32 v247, v89
	v_cvt_pk_bf16_f32 v147, v248, v249
	v_add_f32_e32 v250, v246, v250
	v_add_f32_e32 v251, v247, v251
	v_exp_f32_e32 v248, v90
	v_exp_f32_e32 v249, v91
	v_cvt_pk_bf16_f32 v84, v246, v247
	v_add_f32_e32 v250, v248, v250
	v_add_f32_e32 v251, v249, v251
	v_exp_f32_e32 v246, v92
	v_exp_f32_e32 v247, v93
	v_cvt_pk_bf16_f32 v149, v248, v249
	v_add_f32_e32 v250, v246, v250
	v_add_f32_e32 v251, v247, v251
	v_exp_f32_e32 v248, v94
	v_exp_f32_e32 v249, v95
	v_cvt_pk_bf16_f32 v150, v246, v247
	v_add_f32_e32 v250, v248, v250
	v_add_f32_e32 v251, v249, v251
	v_exp_f32_e32 v246, v64
	v_exp_f32_e32 v247, v65
	v_cvt_pk_bf16_f32 v151, v248, v249
	v_add_f32_e32 v250, v246, v250
	v_add_f32_e32 v251, v247, v251
	v_exp_f32_e32 v248, v66
	v_exp_f32_e32 v249, v67
	v_cvt_pk_bf16_f32 v88, v246, v247
	v_add_f32_e32 v250, v248, v250
	v_add_f32_e32 v251, v249, v251
	v_exp_f32_e32 v246, v68
	v_exp_f32_e32 v247, v69
	v_cvt_pk_bf16_f32 v153, v248, v249
	v_add_f32_e32 v250, v246, v250
	v_add_f32_e32 v251, v247, v251
	v_exp_f32_e32 v248, v70
	v_exp_f32_e32 v249, v71
	v_cvt_pk_bf16_f32 v154, v246, v247
	v_add_f32_e32 v250, v248, v250
	v_add_f32_e32 v251, v249, v251
	v_exp_f32_e32 v246, v72
	v_exp_f32_e32 v247, v73
	v_cvt_pk_bf16_f32 v155, v248, v249
	v_add_f32_e32 v250, v246, v250
	v_add_f32_e32 v251, v247, v251
	v_exp_f32_e32 v248, v74
	v_exp_f32_e32 v249, v75
	v_cvt_pk_bf16_f32 v92, v246, v247
	v_add_f32_e32 v250, v248, v250
	v_add_f32_e32 v251, v249, v251
	v_exp_f32_e32 v246, v76
	v_exp_f32_e32 v247, v77
	v_cvt_pk_bf16_f32 v157, v248, v249
	v_add_f32_e32 v250, v246, v250
	v_add_f32_e32 v251, v247, v251
	v_exp_f32_e32 v248, v78
	v_exp_f32_e32 v249, v79
	v_cvt_pk_bf16_f32 v158, v246, v247
	v_add_f32_e32 v250, v248, v250
	v_add_f32_e32 v251, v249, v251
	v_cvt_pk_bf16_f32 v159, v248, v249
	v_add_f32_e32 v250, v250, v251
	v_add_f32_e32 v176, v176, v250
	s_branch .LBB0_1215

; __global__ void __launch_bounds__(NTHREADS) fwd_megakernel(Params Punused) {
	.amdhsa_kernel _Z14fwd_megakernel6Params
		.amdhsa_group_segment_fixed_size 0
		.amdhsa_private_segment_fixed_size 0
		.amdhsa_kernarg_size 448
		.amdhsa_user_sgpr_count 2
		.amdhsa_user_sgpr_dispatch_ptr 0
		.amdhsa_user_sgpr_queue_ptr 0
		.amdhsa_user_sgpr_kernarg_segment_ptr 1
		.amdhsa_user_sgpr_dispatch_id 0
		.amdhsa_user_sgpr_kernarg_preload_length 0
		.amdhsa_user_sgpr_kernarg_preload_offset 0
		.amdhsa_user_sgpr_private_segment_size 0
		.amdhsa_uses_dynamic_stack 0
		.amdhsa_enable_private_segment 0
		.amdhsa_system_sgpr_workgroup_id_x 1
		.amdhsa_system_sgpr_workgroup_id_y 0
		.amdhsa_system_sgpr_workgroup_id_z 0
		.amdhsa_system_sgpr_workgroup_info 0
		.amdhsa_system_vgpr_workitem_id 2
		.amdhsa_next_free_vgpr 256
		.amdhsa_next_free_sgpr 98
		.amdhsa_accum_offset 256
		.amdhsa_reserve_vcc 1
		.amdhsa_float_round_mode_32 0
		.amdhsa_float_round_mode_16_64 0
		.amdhsa_float_denorm_mode_32 3
		.amdhsa_float_denorm_mode_16_64 3
		.amdhsa_dx10_clamp 1
		.amdhsa_ieee_mode 1
		.amdhsa_fp16_overflow 0
		.amdhsa_tg_split 0
		.amdhsa_exception_fp_ieee_invalid_op 0
		.amdhsa_exception_fp_denorm_src 0
		.amdhsa_exception_fp_ieee_div_zero 0
		.amdhsa_exception_fp_ieee_overflow 0
		.amdhsa_exception_fp_ieee_underflow 0
		.amdhsa_exception_fp_ieee_inexact 0
		.amdhsa_exception_int_div_zero 0
	.end_amdhsa_kernel

; __global__ void __launch_bounds__(NTHREADS) fwd_megakernel(Params Punused) {
amdhsa.kernels:
  - .agpr_count:     0
    .args:
      - .offset:         0
        .size:           192
        .value_kind:     by_value
      - .offset:         192
        .size:           4
        .value_kind:     hidden_block_count_x
      - .offset:         196
        .size:           4
        .value_kind:     hidden_block_count_y
      - .offset:         200
        .size:           4
        .value_kind:     hidden_block_count_z
      - .offset:         204
        .size:           2
        .value_kind:     hidden_group_size_x
      - .offset:         206
        .size:           2
        .value_kind:     hidden_group_size_y
      - .offset:         208
        .size:           2
        .value_kind:     hidden_group_size_z
      - .offset:         210
        .size:           2
        .value_kind:     hidden_remainder_x
      - .offset:         212
        .size:           2
        .value_kind:     hidden_remainder_y
      - .offset:         214
        .size:           2
        .value_kind:     hidden_remainder_z
      - .offset:         232
        .size:           8
        .value_kind:     hidden_global_offset_x
      - .offset:         240
        .size:           8
        .value_kind:     hidden_global_offset_y
      - .offset:         248
        .size:           8
        .value_kind:     hidden_global_offset_z
      - .offset:         256
        .size:           2
        .value_kind:     hidden_grid_dims
      - .offset:         280
        .size:           8
        .value_kind:     hidden_multigrid_sync_arg
      - .offset:         312
        .size:           4
        .value_kind:     hidden_dynamic_lds_size
    .group_segment_fixed_size: 0
    .kernarg_segment_align: 8
    .kernarg_segment_size: 448
    .language:       OpenCL C
    .language_version:
      - 2
      - 0
    .max_flat_workgroup_size: 512
    .name:           _Z14fwd_megakernel6Params
    .private_segment_fixed_size: 0
    .sgpr_count:     104
    .sgpr_spill_count: 0
    .symbol:         _Z14fwd_megakernel6Params.kd
    .uniform_work_group_size: 1
    .uses_dynamic_stack: false
    .vgpr_count:     256
    .vgpr_spill_count: 0
    .wavefront_size: 64
